# SGU mixer MFMA chain: both B fragments of a k-slice read before its first MFMA; attention unit-2 prologue: K fragments of the first QK read back to back with counted waits
# speedup vs baseline: 1.0068x; 1.0026x over previous
.LBB0_131:
	s_or_b64 exec, exec, s[26:27]
	s_waitcnt lgkmcnt(0)
	s_barrier
	ds_read_b64 v[2:3], v171
	s_waitcnt vmcnt(20)
	v_lshlrev_b32_e32 v5, 16, v70
	v_lshlrev_b32_e32 v4, 16, v66
	v_and_b32_e32 v7, 0xffff0000, v70
	v_and_b32_e32 v6, 0xffff0000, v66
	s_waitcnt lgkmcnt(0)
	v_pk_mul_f32 v[4:5], v[2:3], v[4:5]
	v_pk_mul_f32 v[6:7], v[2:3], v[6:7]
	v_cvt_pk_bf16_f32 v4, v4, v5
	v_cvt_pk_bf16_f32 v5, v6, v7
	ds_write2_b32 v176, v4, v5 offset0:128 offset1:196
	v_lshlrev_b32_e32 v5, 16, v71
	v_lshlrev_b32_e32 v4, 16, v67
	v_and_b32_e32 v7, 0xffff0000, v71
	v_and_b32_e32 v6, 0xffff0000, v67
	v_pk_mul_f32 v[4:5], v[2:3], v[4:5]
	v_pk_mul_f32 v[6:7], v[2:3], v[6:7]
	v_cvt_pk_bf16_f32 v4, v4, v5
	v_cvt_pk_bf16_f32 v5, v6, v7
	v_add_u32_e32 v8, 0x400, v176
	ds_write2_b32 v8, v4, v5 offset0:8 offset1:76
	v_lshlrev_b32_e32 v5, 16, v72
	v_lshlrev_b32_e32 v4, 16, v68
	v_and_b32_e32 v7, 0xffff0000, v72
	v_and_b32_e32 v6, 0xffff0000, v68
	v_pk_mul_f32 v[4:5], v[2:3], v[4:5]
	v_pk_mul_f32 v[6:7], v[2:3], v[6:7]
	v_cvt_pk_bf16_f32 v4, v4, v5
	v_cvt_pk_bf16_f32 v5, v6, v7
	ds_write2_b32 v8, v4, v5 offset0:144 offset1:212
	v_lshlrev_b32_e32 v5, 16, v73
	v_lshlrev_b32_e32 v4, 16, v69
	v_and_b32_e32 v7, 0xffff0000, v73
	v_and_b32_e32 v6, 0xffff0000, v69
	v_pk_mul_f32 v[4:5], v[2:3], v[4:5]
	v_pk_mul_f32 v[6:7], v[2:3], v[6:7]
	v_cvt_pk_bf16_f32 v4, v4, v5
	v_cvt_pk_bf16_f32 v5, v6, v7
	v_add_u32_e32 v6, 0x800, v176
	ds_write2_b32 v6, v4, v5 offset0:24 offset1:92
	s_waitcnt vmcnt(18)
	v_lshlrev_b32_e32 v5, 16, v78
	v_lshlrev_b32_e32 v4, 16, v74
	v_and_b32_e32 v7, 0xffff0000, v78
	v_and_b32_e32 v6, 0xffff0000, v74
	v_pk_mul_f32 v[4:5], v[2:3], v[4:5]
	v_pk_mul_f32 v[6:7], v[2:3], v[6:7]
	v_cvt_pk_bf16_f32 v4, v4, v5
	v_cvt_pk_bf16_f32 v5, v6, v7
	ds_write2_b32 v177, v4, v5 offset0:128 offset1:196
	v_lshlrev_b32_e32 v5, 16, v79
	v_lshlrev_b32_e32 v4, 16, v75
	v_and_b32_e32 v7, 0xffff0000, v79
	v_and_b32_e32 v6, 0xffff0000, v75
	v_pk_mul_f32 v[4:5], v[2:3], v[4:5]
	v_pk_mul_f32 v[6:7], v[2:3], v[6:7]
	v_cvt_pk_bf16_f32 v4, v4, v5
	v_cvt_pk_bf16_f32 v5, v6, v7
	v_add_u32_e32 v8, 0x400, v177
	ds_write2_b32 v8, v4, v5 offset0:8 offset1:76
	v_lshlrev_b32_e32 v5, 16, v80
	v_lshlrev_b32_e32 v4, 16, v76
	v_and_b32_e32 v7, 0xffff0000, v80
	v_and_b32_e32 v6, 0xffff0000, v76
	v_pk_mul_f32 v[4:5], v[2:3], v[4:5]
	v_pk_mul_f32 v[6:7], v[2:3], v[6:7]
	v_cvt_pk_bf16_f32 v4, v4, v5
	v_cvt_pk_bf16_f32 v5, v6, v7
	ds_write2_b32 v8, v4, v5 offset0:144 offset1:212
	v_lshlrev_b32_e32 v5, 16, v81
	v_lshlrev_b32_e32 v4, 16, v77
	v_and_b32_e32 v7, 0xffff0000, v81
	v_and_b32_e32 v6, 0xffff0000, v77
	v_pk_mul_f32 v[4:5], v[2:3], v[4:5]
	v_pk_mul_f32 v[2:3], v[2:3], v[6:7]
	v_cvt_pk_bf16_f32 v4, v4, v5
	v_cvt_pk_bf16_f32 v2, v2, v3
	v_add_u32_e32 v3, 0x800, v177
	ds_write2_b32 v3, v4, v2 offset0:24 offset1:92
	s_waitcnt lgkmcnt(0)
	s_barrier
	ds_read_b128 v[2:5], v183 offset:512
	ds_read_b128 v[186:189], v183 offset:544
	s_waitcnt vmcnt(17) lgkmcnt(1)
	v_mfma_f32_32x32x16_bf16 v[18:33], v[82:85], v[2:5], 0
	ds_read_b128 v[2:5], v183 offset:9216
	s_andn2_b64 vcc, exec, s[56:57]
	s_waitcnt vmcnt(16) lgkmcnt(1)
	v_mfma_f32_32x32x16_bf16 v[18:33], v[86:89], v[186:189], v[18:33]
	ds_read_b128 v[186:189], v183 offset:9248
	s_waitcnt lgkmcnt(1)
	v_mfma_f32_32x32x16_bf16 v[2:17], v[82:85], v[2:5], 0
	s_waitcnt lgkmcnt(0)
	v_mfma_f32_32x32x16_bf16 v[2:17], v[86:89], v[186:189], v[2:17]
	s_cbranch_vccnz .LBB0_133
	ds_read_b128 v[186:189], v183 offset:576
	ds_read_b128 v[194:197], v183 offset:9280
	s_waitcnt vmcnt(15) lgkmcnt(1)
	v_mfma_f32_32x32x16_bf16 v[18:33], v[90:93], v[186:189], v[18:33]
	s_waitcnt lgkmcnt(0)
	v_mfma_f32_32x32x16_bf16 v[2:17], v[90:93], v[194:197], v[2:17]

.LBB0_138:
	ds_read_b128 v[186:189], v183 offset:736
	ds_read_b128 v[194:197], v183 offset:9440
	s_waitcnt vmcnt(10) lgkmcnt(1)
	v_mfma_f32_32x32x16_bf16 v[18:33], v[110:113], v[186:189], v[18:33]
	s_waitcnt lgkmcnt(0)
	v_mfma_f32_32x32x16_bf16 v[2:17], v[110:113], v[194:197], v[2:17]

.LBB0_143:
	ds_read_b128 v[186:189], v183 offset:608
	ds_read_b128 v[194:197], v183 offset:9312
	s_waitcnt vmcnt(14) lgkmcnt(1)
	v_mfma_f32_32x32x16_bf16 v[18:33], v[94:97], v[186:189], v[18:33]
	s_waitcnt lgkmcnt(0)
	v_mfma_f32_32x32x16_bf16 v[2:17], v[94:97], v[194:197], v[2:17]
	s_andn2_b64 vcc, exec, s[86:87]
	s_cbranch_vccnz .LBB0_135
.LBB0_144:
	ds_read_b128 v[186:189], v183 offset:640
	ds_read_b128 v[194:197], v183 offset:9344
	s_waitcnt vmcnt(13) lgkmcnt(1)
	v_mfma_f32_32x32x16_bf16 v[18:33], v[98:101], v[186:189], v[18:33]
	s_waitcnt lgkmcnt(0)
	v_mfma_f32_32x32x16_bf16 v[2:17], v[98:101], v[194:197], v[2:17]
	s_andn2_b64 vcc, exec, s[88:89]
	s_cbranch_vccnz .LBB0_136
.LBB0_145:
	ds_read_b128 v[186:189], v183 offset:672
	ds_read_b128 v[194:197], v183 offset:9376
	s_waitcnt vmcnt(12) lgkmcnt(1)
	v_mfma_f32_32x32x16_bf16 v[18:33], v[102:105], v[186:189], v[18:33]
	s_waitcnt lgkmcnt(0)
	v_mfma_f32_32x32x16_bf16 v[2:17], v[102:105], v[194:197], v[2:17]
	v_cndmask_b32_e64 v185, 0, 1, s[90:91]
	v_cmp_ne_u32_e64 s[42:43], 1, v185
	s_andn2_b64 vcc, exec, s[90:91]
	s_cbranch_vccnz .LBB0_137
.LBB0_146:
	ds_read_b128 v[186:189], v183 offset:704
	ds_read_b128 v[194:197], v183 offset:9408
	s_waitcnt vmcnt(11) lgkmcnt(1)
	v_mfma_f32_32x32x16_bf16 v[18:33], v[106:109], v[186:189], v[18:33]
	s_waitcnt lgkmcnt(0)
	v_mfma_f32_32x32x16_bf16 v[2:17], v[106:109], v[194:197], v[2:17]
	s_and_b64 vcc, exec, s[42:43]
	s_cbranch_vccz .LBB0_138
	s_branch .LBB0_139

.LBB0_261:
	s_and_b32 s2, s2, 3
	s_lshl_b32 s11, s46, 7
	s_lshl_b32 s28, s2, 5
	s_or_b32 s16, s28, s11
	v_and_b32_e32 v235, 31, v237
	s_or_b32 s11, s16, s60
	v_or_b32_e32 v6, s11, v235
	v_ashrrev_i32_e32 v7, 31, v6
	v_readlane_b32 s18, v252, 17
	s_ashr_i32 s6, s3, 8
	v_lshlrev_b64 v[6:7], 12, v[6:7]
	v_readlane_b32 s19, v252, 18
	v_and_b32_e32 v238, 63, v237
	v_lshrrev_b32_e32 v234, 5, v238
	v_lshl_add_u64 v[6:7], s[18:19], 0, v[6:7]
	s_lshl_b32 s18, s6, 6
	v_lshl_add_u64 v[6:7], v[6:7], 0, s[84:85]
	s_ashr_i32 s19, s18, 31
	v_lshl_add_u64 v[6:7], s[18:19], 1, v[6:7]
	v_lshlrev_b32_e32 v0, 4, v234
	v_lshl_add_u64 v[6:7], v[6:7], 0, v[0:1]
	global_load_dwordx4 v[146:149], v[6:7], off nt
	global_load_dwordx4 v[150:153], v[6:7], off offset:32 nt
	global_load_dwordx4 v[154:157], v[6:7], off offset:64 nt
	global_load_dwordx4 v[158:161], v[6:7], off offset:96 nt
	s_mov_b64 s[18:19], 0x80
	s_add_i32 m0, s10, 0x10000
	v_lshl_add_u64 v[8:9], v[4:5], 0, s[18:19]
	s_mov_b64 s[18:19], 0x200080
	v_lshl_add_u64 v[4:5], v[4:5], 0, s[18:19]
	global_load_lds_dwordx4 v[8:9], off
	s_add_i32 m0, s10, 0x12000
	v_and_b32_e32 v0, 19, v237
	global_load_lds_dwordx4 v[4:5], off
	v_lshlrev_b32_e32 v3, 1, v237
	v_lshrrev_b32_e32 v38, 1, v2
	v_and_or_b32 v0, v3, 8, v0
	v_and_b32_e32 v22, 4, v38
	v_or_b32_e32 v2, v0, v22
	v_lshl_or_b32 v37, s6, 3, v234
	v_lshlrev_b32_e32 v39, 8, v2
	v_bitop3_b32 v2, v2, v37, 15 bitop3:0x6c
	v_lshl_add_u32 v239, v2, 4, v39
	v_add_u32_e32 v18, 0, v239
	s_waitcnt vmcnt(4)
	s_barrier
	ds_read_b128 v[2:5], v18
	v_bitop3_b32 v0, v0, 15, v22 bitop3:0xc8
	v_bitop3_b32 v22, v37, v0, 2 bitop3:0x36
	v_lshl_add_u32 v240, v22, 4, v39
	v_add_u32_e32 v44, 0, v240
	ds_read_b128 v[40:43], v44
	ds_read_b128 v[18:21], v18 offset:8192
	s_mov_b64 s[26:27], -1
	s_cmpk_lt_u32 s16, 0xb0
	s_waitcnt vmcnt(0) lgkmcnt(0)
	v_mfma_f32_32x32x16_bf16 v[2:17], v[2:5], v[146:149], 0
	v_mfma_f32_32x32x16_bf16 v[2:17], v[40:43], v[150:153], v[2:17]
	ds_read_b128 v[40:43], v44 offset:8192
	v_bitop3_b32 v44, v37, v0, 4 bitop3:0x36
	v_lshl_add_u32 v241, v44, 4, v39
	v_add_u32_e32 v44, 0, v241
	v_bitop3_b32 v0, v37, v0, 6 bitop3:0x36
	v_lshl_add_u32 v242, v0, 4, v39
	v_add_u32_e32 v0, 0, v242
	v_mfma_f32_32x32x16_bf16 v[18:33], v[18:21], v[146:149], 0
	v_or_b32_e32 v37, s16, v235
	ds_read_b128 v[194:197], v44
	ds_read_b128 v[198:201], v44 offset:8192
	ds_read_b128 v[202:205], v0
	ds_read_b128 v[206:209], v0 offset:8192
	s_waitcnt lgkmcnt(4)
	v_mfma_f32_32x32x16_bf16 v[18:33], v[40:43], v[150:153], v[18:33]
	s_waitcnt lgkmcnt(3)
	v_mfma_f32_32x32x16_bf16 v[2:17], v[194:197], v[154:157], v[2:17]
	s_waitcnt lgkmcnt(2)
	v_mfma_f32_32x32x16_bf16 v[18:33], v[198:201], v[154:157], v[18:33]
	s_waitcnt lgkmcnt(1)
	v_mfma_f32_32x32x16_bf16 v[2:17], v[202:205], v[158:161], v[2:17]
	s_waitcnt lgkmcnt(0)
	v_mfma_f32_32x32x16_bf16 v[18:33], v[206:209], v[158:161], v[18:33]
	s_cbranch_scc1 .LBB0_263
	v_or_b32_e32 v0, s16, v235
	s_mov_b64 s[26:27], 0
